# MoE mainloops: static priority raise for odd HW wave slots (skip s_setprio 0 after the MFMA segment)
# baseline (speedup 1.0000x reference)
.LBB0_1185:
	s_add_i32 s5, s5, 64
	s_waitcnt lgkmcnt(0)
	s_barrier
	s_setprio 1
	ds_read_b128 v[226:229], v220
	ds_read_b128 v[246:249], v220 offset:2048
	ds_read_b128 v[230:233], v219 offset:32768
	ds_read_b128 v[234:237], v219 offset:34816
	ds_read_b128 v[238:241], v219 offset:36864
	ds_read_b128 v[242:245], v219 offset:38912
	ds_read_b128 v[214:217], v220 offset:4096
	s_waitcnt lgkmcnt(4)
	v_mfma_f32_16x16x32_bf16 v[156:159], v[226:229], v[230:233], v[156:159]
	s_waitcnt lgkmcnt(3)
	v_mfma_f32_16x16x32_bf16 v[116:119], v[226:229], v[234:237], v[116:119]
	s_waitcnt lgkmcnt(2)
	v_mfma_f32_16x16x32_bf16 v[148:151], v[226:229], v[238:241], v[148:151]
	s_waitcnt lgkmcnt(1)
	v_mfma_f32_16x16x32_bf16 v[112:115], v[226:229], v[242:245], v[112:115]
	ds_read_b128 v[226:229], v220 offset:6144
	v_mfma_f32_16x16x32_bf16 v[108:111], v[246:249], v[230:233], v[108:111]
	v_mfma_f32_16x16x32_bf16 v[100:103], v[246:249], v[234:237], v[100:103]
	v_mfma_f32_16x16x32_bf16 v[104:107], v[246:249], v[238:241], v[104:107]
	v_mfma_f32_16x16x32_bf16 v[96:99], v[246:249], v[242:245], v[96:99]
	ds_read_b128 v[246:249], v220 offset:8192
	s_waitcnt lgkmcnt(2)
	v_mfma_f32_16x16x32_bf16 v[92:95], v[214:217], v[230:233], v[92:95]
	v_mfma_f32_16x16x32_bf16 v[84:87], v[214:217], v[234:237], v[84:87]
	v_mfma_f32_16x16x32_bf16 v[88:91], v[214:217], v[238:241], v[88:91]
	v_mfma_f32_16x16x32_bf16 v[80:83], v[214:217], v[242:245], v[80:83]
	ds_read_b128 v[214:217], v220 offset:10240
	s_waitcnt lgkmcnt(2)
	v_mfma_f32_16x16x32_bf16 v[76:79], v[226:229], v[230:233], v[76:79]
	v_mfma_f32_16x16x32_bf16 v[68:71], v[226:229], v[234:237], v[68:71]
	v_mfma_f32_16x16x32_bf16 v[72:75], v[226:229], v[238:241], v[72:75]
	v_mfma_f32_16x16x32_bf16 v[64:67], v[226:229], v[242:245], v[64:67]
	ds_read_b128 v[226:229], v220 offset:12288
	s_waitcnt lgkmcnt(2)
	v_mfma_f32_16x16x32_bf16 v[60:63], v[246:249], v[230:233], v[60:63]
	v_mfma_f32_16x16x32_bf16 v[52:55], v[246:249], v[234:237], v[52:55]
	v_mfma_f32_16x16x32_bf16 v[56:59], v[246:249], v[238:241], v[56:59]
	v_mfma_f32_16x16x32_bf16 v[48:51], v[246:249], v[242:245], v[48:51]
	ds_read_b128 v[246:249], v220 offset:14336
	s_waitcnt lgkmcnt(2)
	v_mfma_f32_16x16x32_bf16 v[44:47], v[214:217], v[230:233], v[44:47]
	v_mfma_f32_16x16x32_bf16 v[36:39], v[214:217], v[234:237], v[36:39]
	v_mfma_f32_16x16x32_bf16 v[40:43], v[214:217], v[238:241], v[40:43]
	v_mfma_f32_16x16x32_bf16 v[32:35], v[214:217], v[242:245], v[32:35]
	s_waitcnt lgkmcnt(1)
	v_mfma_f32_16x16x32_bf16 v[24:27], v[226:229], v[230:233], v[24:27]
	v_mfma_f32_16x16x32_bf16 v[16:19], v[226:229], v[234:237], v[16:19]
	v_mfma_f32_16x16x32_bf16 v[28:31], v[226:229], v[238:241], v[28:31]
	v_mfma_f32_16x16x32_bf16 v[20:23], v[226:229], v[242:245], v[20:23]
	s_waitcnt lgkmcnt(0)
	v_mfma_f32_16x16x32_bf16 v[8:11], v[246:249], v[230:233], v[8:11]
	v_mfma_f32_16x16x32_bf16 v[0:3], v[246:249], v[234:237], v[0:3]
	v_mfma_f32_16x16x32_bf16 v[12:15], v[246:249], v[238:241], v[12:15]
	v_mfma_f32_16x16x32_bf16 v[4:7], v[246:249], v[242:245], v[4:7]
	ds_read_b128 v[214:217], v222
	ds_read_b128 v[242:245], v222 offset:2048
	ds_read_b128 v[226:229], v221 offset:32768
	ds_read_b128 v[230:233], v221 offset:34816
	ds_read_b128 v[234:237], v221 offset:36864
	ds_read_b128 v[238:241], v221 offset:38912
	ds_read_b128 v[246:249], v222 offset:4096
	s_waitcnt lgkmcnt(4)
	v_mfma_f32_16x16x32_bf16 v[156:159], v[214:217], v[226:229], v[156:159]
	s_waitcnt lgkmcnt(3)
	v_mfma_f32_16x16x32_bf16 v[116:119], v[214:217], v[230:233], v[116:119]
	s_waitcnt lgkmcnt(2)
	v_mfma_f32_16x16x32_bf16 v[148:151], v[214:217], v[234:237], v[148:151]
	s_waitcnt lgkmcnt(1)
	v_mfma_f32_16x16x32_bf16 v[112:115], v[214:217], v[238:241], v[112:115]
	ds_read_b128 v[214:217], v222 offset:6144
	v_mfma_f32_16x16x32_bf16 v[108:111], v[242:245], v[226:229], v[108:111]
	v_mfma_f32_16x16x32_bf16 v[100:103], v[242:245], v[230:233], v[100:103]
	v_mfma_f32_16x16x32_bf16 v[104:107], v[242:245], v[234:237], v[104:107]
	v_mfma_f32_16x16x32_bf16 v[96:99], v[242:245], v[238:241], v[96:99]
	ds_read_b128 v[242:245], v222 offset:8192
	s_waitcnt lgkmcnt(2)
	v_mfma_f32_16x16x32_bf16 v[92:95], v[246:249], v[226:229], v[92:95]
	v_mfma_f32_16x16x32_bf16 v[84:87], v[246:249], v[230:233], v[84:87]
	v_mfma_f32_16x16x32_bf16 v[88:91], v[246:249], v[234:237], v[88:91]
	v_mfma_f32_16x16x32_bf16 v[80:83], v[246:249], v[238:241], v[80:83]
	ds_read_b128 v[246:249], v222 offset:10240
	s_waitcnt lgkmcnt(2)
	v_mfma_f32_16x16x32_bf16 v[76:79], v[214:217], v[226:229], v[76:79]
	v_mfma_f32_16x16x32_bf16 v[68:71], v[214:217], v[230:233], v[68:71]
	v_mfma_f32_16x16x32_bf16 v[72:75], v[214:217], v[234:237], v[72:75]
	v_mfma_f32_16x16x32_bf16 v[64:67], v[214:217], v[238:241], v[64:67]
	ds_read_b128 v[214:217], v222 offset:12288
	s_waitcnt lgkmcnt(2)
	v_mfma_f32_16x16x32_bf16 v[60:63], v[242:245], v[226:229], v[60:63]
	v_mfma_f32_16x16x32_bf16 v[52:55], v[242:245], v[230:233], v[52:55]
	v_mfma_f32_16x16x32_bf16 v[56:59], v[242:245], v[234:237], v[56:59]
	v_mfma_f32_16x16x32_bf16 v[48:51], v[242:245], v[238:241], v[48:51]
	ds_read_b128 v[242:245], v222 offset:14336
	s_waitcnt lgkmcnt(2)
	v_mfma_f32_16x16x32_bf16 v[44:47], v[246:249], v[226:229], v[44:47]
	v_mfma_f32_16x16x32_bf16 v[36:39], v[246:249], v[230:233], v[36:39]
	v_mfma_f32_16x16x32_bf16 v[40:43], v[246:249], v[234:237], v[40:43]
	v_mfma_f32_16x16x32_bf16 v[32:35], v[246:249], v[238:241], v[32:35]
	s_waitcnt lgkmcnt(1)
	v_mfma_f32_16x16x32_bf16 v[24:27], v[214:217], v[226:229], v[24:27]
	v_mfma_f32_16x16x32_bf16 v[16:19], v[214:217], v[230:233], v[16:19]
	v_mfma_f32_16x16x32_bf16 v[28:31], v[214:217], v[234:237], v[28:31]
	v_mfma_f32_16x16x32_bf16 v[20:23], v[214:217], v[238:241], v[20:23]
	s_waitcnt lgkmcnt(0)
	v_mfma_f32_16x16x32_bf16 v[8:11], v[242:245], v[226:229], v[8:11]
	v_mfma_f32_16x16x32_bf16 v[0:3], v[242:245], v[230:233], v[0:3]
	v_mfma_f32_16x16x32_bf16 v[12:15], v[242:245], v[234:237], v[12:15]
	v_mfma_f32_16x16x32_bf16 v[4:7], v[242:245], v[238:241], v[4:7]
	s_getreg_b32 s99, hwreg(HW_REG_HW_ID, 0, 1)
	s_cmp_eq_u32 s99, 1
	s_cbranch_scc1 .Lsp_0
	s_setprio 0
.Lsp_0:
	s_mov_b64 s[10:11], 0x80
	s_andn2_b64 vcc, exec, s[2:3]
	s_mov_b64 s[2:3], 0x80000
	v_lshl_add_u64 v[194:195], v[194:195], 0, s[10:11]
	v_lshl_add_u64 v[212:213], v[212:213], 0, s[2:3]
	s_barrier
	s_cbranch_vccz .LBB0_1183

.LBB0_1244:
	s_waitcnt lgkmcnt(0)
	s_barrier
	s_setprio 1
	ds_read_b128 v[226:229], v218
	ds_read_b128 v[246:249], v218 offset:2048
	ds_read_b128 v[230:233], v217 offset:32768
	ds_read_b128 v[234:237], v217 offset:34816
	ds_read_b128 v[238:241], v217 offset:36864
	ds_read_b128 v[242:245], v217 offset:38912
	ds_read_b128 v[212:215], v218 offset:4096
	s_waitcnt lgkmcnt(4)
	v_mfma_f32_16x16x32_bf16 v[188:191], v[226:229], v[230:233], v[188:191]
	s_waitcnt lgkmcnt(3)
	v_mfma_f32_16x16x32_bf16 v[184:187], v[226:229], v[234:237], v[184:187]
	s_waitcnt lgkmcnt(2)
	v_mfma_f32_16x16x32_bf16 v[180:183], v[226:229], v[238:241], v[180:183]
	s_waitcnt lgkmcnt(1)
	v_mfma_f32_16x16x32_bf16 v[176:179], v[226:229], v[242:245], v[176:179]
	ds_read_b128 v[226:229], v218 offset:6144
	v_mfma_f32_16x16x32_bf16 v[160:163], v[246:249], v[230:233], v[160:163]
	v_mfma_f32_16x16x32_bf16 v[152:155], v[246:249], v[234:237], v[152:155]
	v_mfma_f32_16x16x32_bf16 v[148:151], v[246:249], v[238:241], v[148:151]
	v_mfma_f32_16x16x32_bf16 v[140:143], v[246:249], v[242:245], v[140:143]
	ds_read_b128 v[246:249], v218 offset:8192
	s_waitcnt lgkmcnt(2)
	v_mfma_f32_16x16x32_bf16 v[116:119], v[212:215], v[230:233], v[116:119]
	v_mfma_f32_16x16x32_bf16 v[104:107], v[212:215], v[234:237], v[104:107]
	v_mfma_f32_16x16x32_bf16 v[96:99], v[212:215], v[238:241], v[96:99]
	v_mfma_f32_16x16x32_bf16 v[88:91], v[212:215], v[242:245], v[88:91]
	ds_read_b128 v[212:215], v218 offset:10240
	s_waitcnt lgkmcnt(2)
	v_mfma_f32_16x16x32_bf16 v[76:79], v[226:229], v[230:233], v[76:79]
	v_mfma_f32_16x16x32_bf16 v[72:75], v[226:229], v[234:237], v[72:75]
	v_mfma_f32_16x16x32_bf16 v[68:71], v[226:229], v[238:241], v[68:71]
	v_mfma_f32_16x16x32_bf16 v[64:67], v[226:229], v[242:245], v[64:67]
	ds_read_b128 v[226:229], v218 offset:12288
	s_waitcnt lgkmcnt(2)
	v_mfma_f32_16x16x32_bf16 v[60:63], v[246:249], v[230:233], v[60:63]
	v_mfma_f32_16x16x32_bf16 v[56:59], v[246:249], v[234:237], v[56:59]
	v_mfma_f32_16x16x32_bf16 v[52:55], v[246:249], v[238:241], v[52:55]
	v_mfma_f32_16x16x32_bf16 v[48:51], v[246:249], v[242:245], v[48:51]
	ds_read_b128 v[246:249], v218 offset:14336
	s_waitcnt lgkmcnt(2)
	v_mfma_f32_16x16x32_bf16 v[28:31], v[212:215], v[230:233], v[28:31]
	v_mfma_f32_16x16x32_bf16 v[24:27], v[212:215], v[234:237], v[24:27]
	v_mfma_f32_16x16x32_bf16 v[20:23], v[212:215], v[238:241], v[20:23]
	v_mfma_f32_16x16x32_bf16 v[16:19], v[212:215], v[242:245], v[16:19]
	s_waitcnt lgkmcnt(1)
	v_mfma_f32_16x16x32_bf16 v[44:47], v[226:229], v[230:233], v[44:47]
	v_mfma_f32_16x16x32_bf16 v[40:43], v[226:229], v[234:237], v[40:43]
	v_mfma_f32_16x16x32_bf16 v[36:39], v[226:229], v[238:241], v[36:39]
	v_mfma_f32_16x16x32_bf16 v[32:35], v[226:229], v[242:245], v[32:35]
	s_waitcnt lgkmcnt(0)
	v_mfma_f32_16x16x32_bf16 v[8:11], v[246:249], v[230:233], v[8:11]
	v_mfma_f32_16x16x32_bf16 v[4:7], v[246:249], v[234:237], v[4:7]
	v_mfma_f32_16x16x32_bf16 v[0:3], v[246:249], v[238:241], v[0:3]
	v_mfma_f32_16x16x32_bf16 v[12:15], v[246:249], v[242:245], v[12:15]
	ds_read_b128 v[212:215], v220
	ds_read_b128 v[242:245], v220 offset:2048
	ds_read_b128 v[226:229], v219 offset:32768
	ds_read_b128 v[230:233], v219 offset:34816
	ds_read_b128 v[234:237], v219 offset:36864
	ds_read_b128 v[238:241], v219 offset:38912
	ds_read_b128 v[246:249], v220 offset:4096
	s_waitcnt lgkmcnt(4)
	v_mfma_f32_16x16x32_bf16 v[188:191], v[212:215], v[226:229], v[188:191]
	s_waitcnt lgkmcnt(3)
	v_mfma_f32_16x16x32_bf16 v[184:187], v[212:215], v[230:233], v[184:187]
	s_waitcnt lgkmcnt(2)
	v_mfma_f32_16x16x32_bf16 v[180:183], v[212:215], v[234:237], v[180:183]
	s_waitcnt lgkmcnt(1)
	v_mfma_f32_16x16x32_bf16 v[176:179], v[212:215], v[238:241], v[176:179]
	ds_read_b128 v[212:215], v220 offset:6144
	v_mfma_f32_16x16x32_bf16 v[160:163], v[242:245], v[226:229], v[160:163]
	v_mfma_f32_16x16x32_bf16 v[152:155], v[242:245], v[230:233], v[152:155]
	v_mfma_f32_16x16x32_bf16 v[148:151], v[242:245], v[234:237], v[148:151]
	v_mfma_f32_16x16x32_bf16 v[140:143], v[242:245], v[238:241], v[140:143]
	ds_read_b128 v[242:245], v220 offset:8192
	s_waitcnt lgkmcnt(2)
	v_mfma_f32_16x16x32_bf16 v[116:119], v[246:249], v[226:229], v[116:119]
	v_mfma_f32_16x16x32_bf16 v[104:107], v[246:249], v[230:233], v[104:107]
	v_mfma_f32_16x16x32_bf16 v[96:99], v[246:249], v[234:237], v[96:99]
	v_mfma_f32_16x16x32_bf16 v[88:91], v[246:249], v[238:241], v[88:91]
	ds_read_b128 v[246:249], v220 offset:10240
	s_waitcnt lgkmcnt(2)
	v_mfma_f32_16x16x32_bf16 v[76:79], v[212:215], v[226:229], v[76:79]
	v_mfma_f32_16x16x32_bf16 v[72:75], v[212:215], v[230:233], v[72:75]
	v_mfma_f32_16x16x32_bf16 v[68:71], v[212:215], v[234:237], v[68:71]
	v_mfma_f32_16x16x32_bf16 v[64:67], v[212:215], v[238:241], v[64:67]
	ds_read_b128 v[212:215], v220 offset:12288
	s_waitcnt lgkmcnt(2)
	v_mfma_f32_16x16x32_bf16 v[60:63], v[242:245], v[226:229], v[60:63]
	v_mfma_f32_16x16x32_bf16 v[56:59], v[242:245], v[230:233], v[56:59]
	v_mfma_f32_16x16x32_bf16 v[52:55], v[242:245], v[234:237], v[52:55]
	v_mfma_f32_16x16x32_bf16 v[48:51], v[242:245], v[238:241], v[48:51]
	ds_read_b128 v[242:245], v220 offset:14336
	s_waitcnt lgkmcnt(2)
	v_mfma_f32_16x16x32_bf16 v[28:31], v[246:249], v[226:229], v[28:31]
	v_mfma_f32_16x16x32_bf16 v[24:27], v[246:249], v[230:233], v[24:27]
	v_mfma_f32_16x16x32_bf16 v[20:23], v[246:249], v[234:237], v[20:23]
	v_mfma_f32_16x16x32_bf16 v[16:19], v[246:249], v[238:241], v[16:19]
	s_waitcnt lgkmcnt(1)
	v_mfma_f32_16x16x32_bf16 v[44:47], v[212:215], v[226:229], v[44:47]
	v_mfma_f32_16x16x32_bf16 v[40:43], v[212:215], v[230:233], v[40:43]
	v_mfma_f32_16x16x32_bf16 v[36:39], v[212:215], v[234:237], v[36:39]
	v_mfma_f32_16x16x32_bf16 v[32:35], v[212:215], v[238:241], v[32:35]
	s_waitcnt lgkmcnt(0)
	v_mfma_f32_16x16x32_bf16 v[8:11], v[242:245], v[226:229], v[8:11]
	v_mfma_f32_16x16x32_bf16 v[4:7], v[242:245], v[230:233], v[4:7]
	v_mfma_f32_16x16x32_bf16 v[0:3], v[242:245], v[234:237], v[0:3]
	v_mfma_f32_16x16x32_bf16 v[12:15], v[242:245], v[238:241], v[12:15]
	s_getreg_b32 s99, hwreg(HW_REG_HW_ID, 0, 1)
	s_cmp_eq_u32 s99, 1
	s_cbranch_scc1 .Lsp_1
	s_setprio 0
.Lsp_1:
	s_mov_b64 s[10:11], 0x40000
	v_lshl_add_u64 v[194:195], v[194:195], 0, s[0:1]
	v_lshl_add_u64 v[196:197], v[196:197], 0, s[0:1]
	v_lshl_add_u64 v[198:199], v[198:199], 0, s[0:1]
	v_lshl_add_u64 v[200:201], v[200:201], 0, s[0:1]
	v_lshl_add_u64 v[202:203], v[202:203], 0, s[0:1]
	v_lshl_add_u64 v[204:205], v[204:205], 0, s[0:1]
	v_lshl_add_u64 v[206:207], v[206:207], 0, s[0:1]
	v_lshl_add_u64 v[208:209], v[208:209], 0, s[0:1]
	v_lshl_add_u64 v[210:211], v[210:211], 0, s[10:11]
	s_andn2_b64 vcc, exec, s[2:3]
	s_add_i32 s5, s5, 64
	s_barrier
	s_cbranch_vccz .LBB0_1242

.LBB0_2218:
	s_add_i32 s7, s7, 64
	s_waitcnt lgkmcnt(0)
	s_barrier
	s_setprio 1
	ds_read_b128 v[226:229], v220
	ds_read_b128 v[246:249], v220 offset:2048
	ds_read_b128 v[230:233], v219 offset:32768
	ds_read_b128 v[234:237], v219 offset:34816
	ds_read_b128 v[238:241], v219 offset:36864
	ds_read_b128 v[242:245], v219 offset:38912
	ds_read_b128 v[214:217], v220 offset:4096
	s_waitcnt lgkmcnt(4)
	v_mfma_f32_16x16x32_bf16 v[188:191], v[226:229], v[230:233], v[188:191]
	s_waitcnt lgkmcnt(3)
	v_mfma_f32_16x16x32_bf16 v[180:183], v[226:229], v[234:237], v[180:183]
	s_waitcnt lgkmcnt(2)
	v_mfma_f32_16x16x32_bf16 v[184:187], v[226:229], v[238:241], v[184:187]
	s_waitcnt lgkmcnt(1)
	v_mfma_f32_16x16x32_bf16 v[176:179], v[226:229], v[242:245], v[176:179]
	ds_read_b128 v[226:229], v220 offset:6144
	v_mfma_f32_16x16x32_bf16 v[144:147], v[246:249], v[230:233], v[144:147]
	v_mfma_f32_16x16x32_bf16 v[104:107], v[246:249], v[234:237], v[104:107]
	v_mfma_f32_16x16x32_bf16 v[136:139], v[246:249], v[238:241], v[136:139]
	v_mfma_f32_16x16x32_bf16 v[96:99], v[246:249], v[242:245], v[96:99]
	ds_read_b128 v[246:249], v220 offset:8192
	s_waitcnt lgkmcnt(2)
	v_mfma_f32_16x16x32_bf16 v[92:95], v[214:217], v[230:233], v[92:95]
	v_mfma_f32_16x16x32_bf16 v[84:87], v[214:217], v[234:237], v[84:87]
	v_mfma_f32_16x16x32_bf16 v[88:91], v[214:217], v[238:241], v[88:91]
	v_mfma_f32_16x16x32_bf16 v[80:83], v[214:217], v[242:245], v[80:83]
	ds_read_b128 v[214:217], v220 offset:10240
	s_waitcnt lgkmcnt(2)
	v_mfma_f32_16x16x32_bf16 v[76:79], v[226:229], v[230:233], v[76:79]
	v_mfma_f32_16x16x32_bf16 v[68:71], v[226:229], v[234:237], v[68:71]
	v_mfma_f32_16x16x32_bf16 v[72:75], v[226:229], v[238:241], v[72:75]
	v_mfma_f32_16x16x32_bf16 v[64:67], v[226:229], v[242:245], v[64:67]
	ds_read_b128 v[226:229], v220 offset:12288
	s_waitcnt lgkmcnt(2)
	v_mfma_f32_16x16x32_bf16 v[60:63], v[246:249], v[230:233], v[60:63]
	v_mfma_f32_16x16x32_bf16 v[52:55], v[246:249], v[234:237], v[52:55]
	v_mfma_f32_16x16x32_bf16 v[56:59], v[246:249], v[238:241], v[56:59]
	v_mfma_f32_16x16x32_bf16 v[48:51], v[246:249], v[242:245], v[48:51]
	ds_read_b128 v[246:249], v220 offset:14336
	s_waitcnt lgkmcnt(2)
	v_mfma_f32_16x16x32_bf16 v[44:47], v[214:217], v[230:233], v[44:47]
	v_mfma_f32_16x16x32_bf16 v[28:31], v[214:217], v[234:237], v[28:31]
	v_mfma_f32_16x16x32_bf16 v[40:43], v[214:217], v[238:241], v[40:43]
	v_mfma_f32_16x16x32_bf16 v[24:27], v[214:217], v[242:245], v[24:27]
	s_waitcnt lgkmcnt(1)
	v_mfma_f32_16x16x32_bf16 v[32:35], v[226:229], v[230:233], v[32:35]
	v_mfma_f32_16x16x32_bf16 v[16:19], v[226:229], v[234:237], v[16:19]
	v_mfma_f32_16x16x32_bf16 v[36:39], v[226:229], v[238:241], v[36:39]
	v_mfma_f32_16x16x32_bf16 v[20:23], v[226:229], v[242:245], v[20:23]
	s_waitcnt lgkmcnt(0)
	v_mfma_f32_16x16x32_bf16 v[8:11], v[246:249], v[230:233], v[8:11]
	v_mfma_f32_16x16x32_bf16 v[0:3], v[246:249], v[234:237], v[0:3]
	v_mfma_f32_16x16x32_bf16 v[12:15], v[246:249], v[238:241], v[12:15]
	v_mfma_f32_16x16x32_bf16 v[4:7], v[246:249], v[242:245], v[4:7]
	ds_read_b128 v[214:217], v222
	ds_read_b128 v[242:245], v222 offset:2048
	ds_read_b128 v[226:229], v221 offset:32768
	ds_read_b128 v[230:233], v221 offset:34816
	ds_read_b128 v[234:237], v221 offset:36864
	ds_read_b128 v[238:241], v221 offset:38912
	ds_read_b128 v[246:249], v222 offset:4096
	s_waitcnt lgkmcnt(4)
	v_mfma_f32_16x16x32_bf16 v[188:191], v[214:217], v[226:229], v[188:191]
	s_waitcnt lgkmcnt(3)
	v_mfma_f32_16x16x32_bf16 v[180:183], v[214:217], v[230:233], v[180:183]
	s_waitcnt lgkmcnt(2)
	v_mfma_f32_16x16x32_bf16 v[184:187], v[214:217], v[234:237], v[184:187]
	s_waitcnt lgkmcnt(1)
	v_mfma_f32_16x16x32_bf16 v[176:179], v[214:217], v[238:241], v[176:179]
	ds_read_b128 v[214:217], v222 offset:6144
	v_mfma_f32_16x16x32_bf16 v[144:147], v[242:245], v[226:229], v[144:147]
	v_mfma_f32_16x16x32_bf16 v[104:107], v[242:245], v[230:233], v[104:107]
	v_mfma_f32_16x16x32_bf16 v[136:139], v[242:245], v[234:237], v[136:139]
	v_mfma_f32_16x16x32_bf16 v[96:99], v[242:245], v[238:241], v[96:99]
	ds_read_b128 v[242:245], v222 offset:8192
	s_waitcnt lgkmcnt(2)
	v_mfma_f32_16x16x32_bf16 v[92:95], v[246:249], v[226:229], v[92:95]
	v_mfma_f32_16x16x32_bf16 v[84:87], v[246:249], v[230:233], v[84:87]
	v_mfma_f32_16x16x32_bf16 v[88:91], v[246:249], v[234:237], v[88:91]
	v_mfma_f32_16x16x32_bf16 v[80:83], v[246:249], v[238:241], v[80:83]
	ds_read_b128 v[246:249], v222 offset:10240
	s_waitcnt lgkmcnt(2)
	v_mfma_f32_16x16x32_bf16 v[76:79], v[214:217], v[226:229], v[76:79]
	v_mfma_f32_16x16x32_bf16 v[68:71], v[214:217], v[230:233], v[68:71]
	v_mfma_f32_16x16x32_bf16 v[72:75], v[214:217], v[234:237], v[72:75]
	v_mfma_f32_16x16x32_bf16 v[64:67], v[214:217], v[238:241], v[64:67]
	ds_read_b128 v[214:217], v222 offset:12288
	s_waitcnt lgkmcnt(2)
	v_mfma_f32_16x16x32_bf16 v[60:63], v[242:245], v[226:229], v[60:63]
	v_mfma_f32_16x16x32_bf16 v[52:55], v[242:245], v[230:233], v[52:55]
	v_mfma_f32_16x16x32_bf16 v[56:59], v[242:245], v[234:237], v[56:59]
	v_mfma_f32_16x16x32_bf16 v[48:51], v[242:245], v[238:241], v[48:51]
	ds_read_b128 v[242:245], v222 offset:14336
	s_waitcnt lgkmcnt(2)
	v_mfma_f32_16x16x32_bf16 v[44:47], v[246:249], v[226:229], v[44:47]
	v_mfma_f32_16x16x32_bf16 v[28:31], v[246:249], v[230:233], v[28:31]
	v_mfma_f32_16x16x32_bf16 v[40:43], v[246:249], v[234:237], v[40:43]
	v_mfma_f32_16x16x32_bf16 v[24:27], v[246:249], v[238:241], v[24:27]
	s_waitcnt lgkmcnt(1)
	v_mfma_f32_16x16x32_bf16 v[32:35], v[214:217], v[226:229], v[32:35]
	v_mfma_f32_16x16x32_bf16 v[16:19], v[214:217], v[230:233], v[16:19]
	v_mfma_f32_16x16x32_bf16 v[36:39], v[214:217], v[234:237], v[36:39]
	v_mfma_f32_16x16x32_bf16 v[20:23], v[214:217], v[238:241], v[20:23]
	s_waitcnt lgkmcnt(0)
	v_mfma_f32_16x16x32_bf16 v[8:11], v[242:245], v[226:229], v[8:11]
	v_mfma_f32_16x16x32_bf16 v[0:3], v[242:245], v[230:233], v[0:3]
	v_mfma_f32_16x16x32_bf16 v[12:15], v[242:245], v[234:237], v[12:15]
	v_mfma_f32_16x16x32_bf16 v[4:7], v[242:245], v[238:241], v[4:7]
	s_getreg_b32 s99, hwreg(HW_REG_HW_ID, 0, 1)
	s_cmp_eq_u32 s99, 1
	s_cbranch_scc1 .Lsp_2
	s_setprio 0
.Lsp_2:
	v_lshl_add_u64 v[194:195], v[194:195], 0, s[2:3]
	s_andn2_b64 vcc, exec, s[10:11]
	v_lshl_add_u64 v[212:213], v[212:213], 0, s[4:5]
	s_barrier
	s_cbranch_vccz .LBB0_2216

.LBB0_2277:
	s_waitcnt lgkmcnt(0)
	s_barrier
	s_setprio 1
	ds_read_b128 v[226:229], v218
	ds_read_b128 v[246:249], v218 offset:2048
	ds_read_b128 v[230:233], v217 offset:32768
	ds_read_b128 v[234:237], v217 offset:34816
	ds_read_b128 v[238:241], v217 offset:36864
	ds_read_b128 v[242:245], v217 offset:38912
	ds_read_b128 v[212:215], v218 offset:4096
	s_waitcnt lgkmcnt(4)
	v_mfma_f32_16x16x32_bf16 v[188:191], v[226:229], v[230:233], v[188:191]
	s_waitcnt lgkmcnt(3)
	v_mfma_f32_16x16x32_bf16 v[184:187], v[226:229], v[234:237], v[184:187]
	s_waitcnt lgkmcnt(2)
	v_mfma_f32_16x16x32_bf16 v[180:183], v[226:229], v[238:241], v[180:183]
	s_waitcnt lgkmcnt(1)
	v_mfma_f32_16x16x32_bf16 v[176:179], v[226:229], v[242:245], v[176:179]
	ds_read_b128 v[226:229], v218 offset:6144
	v_mfma_f32_16x16x32_bf16 v[168:171], v[246:249], v[230:233], v[168:171]
	v_mfma_f32_16x16x32_bf16 v[156:159], v[246:249], v[234:237], v[156:159]
	v_mfma_f32_16x16x32_bf16 v[148:151], v[246:249], v[238:241], v[148:151]
	v_mfma_f32_16x16x32_bf16 v[144:147], v[246:249], v[242:245], v[144:147]
	ds_read_b128 v[246:249], v218 offset:8192
	s_waitcnt lgkmcnt(2)
	v_mfma_f32_16x16x32_bf16 v[108:111], v[212:215], v[230:233], v[108:111]
	v_mfma_f32_16x16x32_bf16 v[100:103], v[212:215], v[234:237], v[100:103]
	v_mfma_f32_16x16x32_bf16 v[92:95], v[212:215], v[238:241], v[92:95]
	v_mfma_f32_16x16x32_bf16 v[80:83], v[212:215], v[242:245], v[80:83]
	ds_read_b128 v[212:215], v218 offset:10240
	s_waitcnt lgkmcnt(2)
	v_mfma_f32_16x16x32_bf16 v[76:79], v[226:229], v[230:233], v[76:79]
	v_mfma_f32_16x16x32_bf16 v[72:75], v[226:229], v[234:237], v[72:75]
	v_mfma_f32_16x16x32_bf16 v[68:71], v[226:229], v[238:241], v[68:71]
	v_mfma_f32_16x16x32_bf16 v[64:67], v[226:229], v[242:245], v[64:67]
	ds_read_b128 v[226:229], v218 offset:12288
	s_waitcnt lgkmcnt(2)
	v_mfma_f32_16x16x32_bf16 v[60:63], v[246:249], v[230:233], v[60:63]
	v_mfma_f32_16x16x32_bf16 v[56:59], v[246:249], v[234:237], v[56:59]
	v_mfma_f32_16x16x32_bf16 v[52:55], v[246:249], v[238:241], v[52:55]
	v_mfma_f32_16x16x32_bf16 v[48:51], v[246:249], v[242:245], v[48:51]
	ds_read_b128 v[246:249], v218 offset:14336
	s_waitcnt lgkmcnt(2)
	v_mfma_f32_16x16x32_bf16 v[28:31], v[212:215], v[230:233], v[28:31]
	v_mfma_f32_16x16x32_bf16 v[24:27], v[212:215], v[234:237], v[24:27]
	v_mfma_f32_16x16x32_bf16 v[20:23], v[212:215], v[238:241], v[20:23]
	v_mfma_f32_16x16x32_bf16 v[16:19], v[212:215], v[242:245], v[16:19]
	s_waitcnt lgkmcnt(1)
	v_mfma_f32_16x16x32_bf16 v[44:47], v[226:229], v[230:233], v[44:47]
	v_mfma_f32_16x16x32_bf16 v[40:43], v[226:229], v[234:237], v[40:43]
	v_mfma_f32_16x16x32_bf16 v[36:39], v[226:229], v[238:241], v[36:39]
	v_mfma_f32_16x16x32_bf16 v[32:35], v[226:229], v[242:245], v[32:35]
	s_waitcnt lgkmcnt(0)
	v_mfma_f32_16x16x32_bf16 v[8:11], v[246:249], v[230:233], v[8:11]
	v_mfma_f32_16x16x32_bf16 v[4:7], v[246:249], v[234:237], v[4:7]
	v_mfma_f32_16x16x32_bf16 v[0:3], v[246:249], v[238:241], v[0:3]
	v_mfma_f32_16x16x32_bf16 v[12:15], v[246:249], v[242:245], v[12:15]
	ds_read_b128 v[212:215], v220
	ds_read_b128 v[242:245], v220 offset:2048
	ds_read_b128 v[226:229], v219 offset:32768
	ds_read_b128 v[230:233], v219 offset:34816
	ds_read_b128 v[234:237], v219 offset:36864
	ds_read_b128 v[238:241], v219 offset:38912
	ds_read_b128 v[246:249], v220 offset:4096
	s_waitcnt lgkmcnt(4)
	v_mfma_f32_16x16x32_bf16 v[188:191], v[212:215], v[226:229], v[188:191]
	s_waitcnt lgkmcnt(3)
	v_mfma_f32_16x16x32_bf16 v[184:187], v[212:215], v[230:233], v[184:187]
	s_waitcnt lgkmcnt(2)
	v_mfma_f32_16x16x32_bf16 v[180:183], v[212:215], v[234:237], v[180:183]
	s_waitcnt lgkmcnt(1)
	v_mfma_f32_16x16x32_bf16 v[176:179], v[212:215], v[238:241], v[176:179]
	ds_read_b128 v[212:215], v220 offset:6144
	v_mfma_f32_16x16x32_bf16 v[168:171], v[242:245], v[226:229], v[168:171]
	v_mfma_f32_16x16x32_bf16 v[156:159], v[242:245], v[230:233], v[156:159]
	v_mfma_f32_16x16x32_bf16 v[148:151], v[242:245], v[234:237], v[148:151]
	v_mfma_f32_16x16x32_bf16 v[144:147], v[242:245], v[238:241], v[144:147]
	ds_read_b128 v[242:245], v220 offset:8192
	s_waitcnt lgkmcnt(2)
	v_mfma_f32_16x16x32_bf16 v[108:111], v[246:249], v[226:229], v[108:111]
	v_mfma_f32_16x16x32_bf16 v[100:103], v[246:249], v[230:233], v[100:103]
	v_mfma_f32_16x16x32_bf16 v[92:95], v[246:249], v[234:237], v[92:95]
	v_mfma_f32_16x16x32_bf16 v[80:83], v[246:249], v[238:241], v[80:83]
	ds_read_b128 v[246:249], v220 offset:10240
	s_waitcnt lgkmcnt(2)
	v_mfma_f32_16x16x32_bf16 v[76:79], v[212:215], v[226:229], v[76:79]
	v_mfma_f32_16x16x32_bf16 v[72:75], v[212:215], v[230:233], v[72:75]
	v_mfma_f32_16x16x32_bf16 v[68:71], v[212:215], v[234:237], v[68:71]
	v_mfma_f32_16x16x32_bf16 v[64:67], v[212:215], v[238:241], v[64:67]
	ds_read_b128 v[212:215], v220 offset:12288
	s_waitcnt lgkmcnt(2)
	v_mfma_f32_16x16x32_bf16 v[60:63], v[242:245], v[226:229], v[60:63]
	v_mfma_f32_16x16x32_bf16 v[56:59], v[242:245], v[230:233], v[56:59]
	v_mfma_f32_16x16x32_bf16 v[52:55], v[242:245], v[234:237], v[52:55]
	v_mfma_f32_16x16x32_bf16 v[48:51], v[242:245], v[238:241], v[48:51]
	ds_read_b128 v[242:245], v220 offset:14336
	s_waitcnt lgkmcnt(2)
	v_mfma_f32_16x16x32_bf16 v[28:31], v[246:249], v[226:229], v[28:31]
	v_mfma_f32_16x16x32_bf16 v[24:27], v[246:249], v[230:233], v[24:27]
	v_mfma_f32_16x16x32_bf16 v[20:23], v[246:249], v[234:237], v[20:23]
	v_mfma_f32_16x16x32_bf16 v[16:19], v[246:249], v[238:241], v[16:19]
	s_waitcnt lgkmcnt(1)
	v_mfma_f32_16x16x32_bf16 v[44:47], v[212:215], v[226:229], v[44:47]
	v_mfma_f32_16x16x32_bf16 v[40:43], v[212:215], v[230:233], v[40:43]
	v_mfma_f32_16x16x32_bf16 v[36:39], v[212:215], v[234:237], v[36:39]
	v_mfma_f32_16x16x32_bf16 v[32:35], v[212:215], v[238:241], v[32:35]
	s_waitcnt lgkmcnt(0)
	v_mfma_f32_16x16x32_bf16 v[8:11], v[242:245], v[226:229], v[8:11]
	v_mfma_f32_16x16x32_bf16 v[4:7], v[242:245], v[230:233], v[4:7]
	v_mfma_f32_16x16x32_bf16 v[0:3], v[242:245], v[234:237], v[0:3]
	v_mfma_f32_16x16x32_bf16 v[12:15], v[242:245], v[238:241], v[12:15]
	s_getreg_b32 s99, hwreg(HW_REG_HW_ID, 0, 1)
	s_cmp_eq_u32 s99, 1
	s_cbranch_scc1 .Lsp_3
	s_setprio 0
.Lsp_3:
	v_lshl_add_u64 v[194:195], v[194:195], 0, s[0:1]
	v_lshl_add_u64 v[196:197], v[196:197], 0, s[0:1]
	v_lshl_add_u64 v[198:199], v[198:199], 0, s[0:1]
	v_lshl_add_u64 v[200:201], v[200:201], 0, s[0:1]
	v_lshl_add_u64 v[202:203], v[202:203], 0, s[0:1]
	v_lshl_add_u64 v[204:205], v[204:205], 0, s[0:1]
	v_lshl_add_u64 v[206:207], v[206:207], 0, s[0:1]
	v_lshl_add_u64 v[208:209], v[208:209], 0, s[0:1]
	v_lshl_add_u64 v[210:211], v[210:211], 0, s[2:3]
	s_andn2_b64 vcc, exec, s[10:11]
	s_add_i32 s5, s5, 64
	s_barrier
	s_cbranch_vccz .LBB0_2275
